# postA row loop: three 16-lane xor-butterfly all-reduces via DPP adds instead of ds_bpermute round trips (on top of the packed up-GEMM epilogue)
# speedup vs baseline: 1.0052x; 1.0014x over previous
.LBB0_371:
	s_waitcnt vmcnt(0)
	v_lshlrev_b32_e32 v78, 16, v74
	v_and_b32_e32 v79, 0xffff0000, v74
	v_pk_mul_f32 v[80:81], v[78:79], v[78:79]
	v_lshlrev_b32_e32 v84, 16, v75
	v_and_b32_e32 v85, 0xffff0000, v75
	v_pk_mul_f32 v[86:87], v[84:85], v[84:85]
	v_add_f32_e32 v3, v80, v81
	v_lshlrev_b32_e32 v88, 16, v76
	v_and_b32_e32 v89, 0xffff0000, v76
	v_add_f32_e32 v3, v86, v3
	v_pk_mul_f32 v[90:91], v[88:89], v[88:89]
	v_add_f32_e32 v3, v87, v3
	v_lshlrev_b32_e32 v92, 16, v77
	v_and_b32_e32 v93, 0xffff0000, v77
	v_add_f32_e32 v3, v90, v3
	v_pk_mul_f32 v[94:95], v[92:93], v[92:93]
	v_add_f32_e32 v3, v91, v3
	v_add_f32_e32 v3, v94, v3
	v_add_f32_e32 v3, v95, v3
	s_nop 1
	s_waitcnt lgkmcnt(0)
	v_add_f32_dpp v3, v3, v3 quad_perm:[1,0,3,2] row_mask:0xf bank_mask:0xf
	s_nop 1
	s_waitcnt lgkmcnt(0)
	v_add_f32_dpp v3, v3, v3 quad_perm:[2,3,0,1] row_mask:0xf bank_mask:0xf
	s_nop 1
	s_waitcnt lgkmcnt(0)
	v_add_f32_dpp v3, v3, v3 row_half_mirror row_mask:0xf bank_mask:0xf
	s_nop 1
	s_waitcnt lgkmcnt(0)
	v_add_f32_dpp v3, v3, v3 row_mirror row_mask:0xf bank_mask:0xf
	v_fmamk_f32 v3, v3, 0x3c000000, v224
	v_mul_f32_e32 v5, 0x4f800000, v3
	v_cmp_gt_f32_e32 vcc, s33, v3
	s_nop 1
	v_cndmask_b32_e32 v3, v3, v5, vcc
	v_sqrt_f32_e32 v5, v3
	s_nop 0
	v_add_u32_e32 v7, -1, v5
	v_add_u32_e32 v9, 1, v5
	v_fma_f32 v11, -v7, v5, v3
	v_fma_f32 v13, -v9, v5, v3
	v_cmp_ge_f32_e64 s[46:47], 0, v11
	s_nop 1
	v_cndmask_b32_e64 v5, v5, v7, s[46:47]
	v_cmp_lt_f32_e64 s[46:47], 0, v13
	s_nop 1
	v_cndmask_b32_e64 v5, v5, v9, s[46:47]
	v_mul_f32_e32 v7, 0x37800000, v5
	v_cndmask_b32_e32 v5, v5, v7, vcc
	v_cmp_class_f32_e32 vcc, v3, v225
	s_nop 1
	v_cndmask_b32_e32 v3, v5, v3, vcc
	v_div_scale_f32 v5, s[6:7], v3, v3, 1.0
	v_rcp_f32_e32 v7, v5
	v_div_scale_f32 v9, vcc, 1.0, v3, 1.0
	v_fma_f32 v11, -v5, v7, 1.0
	v_fmac_f32_e32 v7, v11, v7
	v_mul_f32_e32 v11, v9, v7
	v_fma_f32 v13, -v5, v11, v9
	v_fmac_f32_e32 v11, v13, v7
	v_fma_f32 v5, -v5, v11, v9
	v_div_fmas_f32 v5, v5, v7, v11
	v_div_fixup_f32 v86, v5, v3, 1.0
	v_pk_mul_f32 v[78:79], v[86:87], v[78:79] op_sel_hi:[0,1]
	v_pk_mul_f32 v[84:85], v[86:87], v[84:85] op_sel_hi:[0,1]
	v_pk_mul_f32 v[80:81], v[54:55], v[78:79]
	v_pk_mul_f32 v[78:79], v[56:57], v[84:85]
	v_pk_mul_f32 v[84:85], v[86:87], v[88:89] op_sel_hi:[0,1]
	v_pk_mul_f32 v[86:87], v[86:87], v[92:93] op_sel_hi:[0,1]
	v_cndmask_b32_e64 v3, 0, 1, s[20:21]
	v_pk_mul_f32 v[84:85], v[50:51], v[84:85]
	v_cmp_ne_u32_e64 s[46:47], 1, v3
	s_andn2_b64 vcc, exec, s[20:21]
	v_pk_mul_f32 v[86:87], v[52:53], v[86:87]
	s_cbranch_vccnz .LBB0_373
	ds_bpermute_b32 v88, v149, v80
	ds_bpermute_b32 v89, v149, v81
	v_mov_b32_e32 v92, v59
	v_mov_b32_e32 v93, v61
	v_mov_b32_e32 v90, v58
	v_mov_b32_e32 v91, v60
	s_waitcnt lgkmcnt(0)
	v_pk_mul_f32 v[88:89], v[92:93], v[88:89]
	v_mov_b32_e32 v92, v63
	v_cndmask_b32_e64 v89, v89, -v89, s[42:43]
	v_cndmask_b32_e64 v88, v88, -v88, s[42:43]
	v_pk_fma_f32 v[80:81], v[90:91], v[80:81], v[88:89]
	ds_bpermute_b32 v88, v149, v78
	ds_bpermute_b32 v89, v149, v79
	v_mov_b32_e32 v93, v65
	v_mov_b32_e32 v90, v62
	v_mov_b32_e32 v91, v64
	s_waitcnt lgkmcnt(0)
	v_pk_mul_f32 v[88:89], v[92:93], v[88:89]
	s_nop 0
	v_cndmask_b32_e64 v89, v89, -v89, s[42:43]
	v_cndmask_b32_e64 v88, v88, -v88, s[42:43]
	v_pk_fma_f32 v[78:79], v[90:91], v[78:79], v[88:89]
	ds_bpermute_b32 v88, v149, v84
	ds_bpermute_b32 v89, v149, v85
	v_mov_b32_e32 v92, v67
	v_mov_b32_e32 v93, v69
	v_mov_b32_e32 v90, v66
	v_mov_b32_e32 v91, v68
	s_waitcnt lgkmcnt(0)
	v_pk_mul_f32 v[88:89], v[92:93], v[88:89]
	v_mov_b32_e32 v92, v71
	v_cndmask_b32_e64 v89, v89, -v89, s[42:43]
	v_cndmask_b32_e64 v88, v88, -v88, s[42:43]
	v_pk_fma_f32 v[84:85], v[90:91], v[84:85], v[88:89]
	ds_bpermute_b32 v88, v149, v86
	ds_bpermute_b32 v89, v149, v87
	v_mov_b32_e32 v93, v73
	v_mov_b32_e32 v90, v70
	v_mov_b32_e32 v91, v72
	s_waitcnt lgkmcnt(0)
	v_pk_mul_f32 v[88:89], v[92:93], v[88:89]
	s_nop 0
	v_cndmask_b32_e64 v89, v89, -v89, s[42:43]
	v_cndmask_b32_e64 v88, v88, -v88, s[42:43]
	v_pk_fma_f32 v[86:87], v[90:91], v[86:87], v[88:89]

.LBB0_378:
	v_add_co_u32_e32 v78, vcc, 0x21e24000, v82
	s_and_b64 s[8:9], exec, s[48:49]
	s_nop 0
	v_addc_co_u32_e32 v79, vcc, 0, v83, vcc
	global_load_dwordx4 v[136:139], v[78:79], off
	s_mov_b32 s7, 0x21e26000
	v_add_co_u32_e32 v84, vcc, s7, v82
	s_movk_i32 s7, 0xfff
	s_cselect_b32 s5, s6, s5
	s_cselect_b32 s8, 0xff, s7
	s_cmp_eq_u32 s5, 0
	s_cselect_b64 s[70:71], -1, 0
	s_and_b64 s[6:7], s[70:71], exec
	v_addc_co_u32_e32 v85, vcc, 0, v83, vcc
	s_cselect_b32 s6, 0, 0xffffd800
	s_cselect_b32 s7, 0, -1
	s_cmp_lt_u32 s5, s8
	v_add_co_u32_e32 v86, vcc, 0x21e25000, v82
	s_cselect_b64 s[72:73], -1, 0
	s_nop 0
	v_addc_co_u32_e32 v87, vcc, 0, v83, vcc
	v_lshl_add_u64 v[88:89], v[82:83], 0, s[6:7]
	s_and_b64 s[6:7], s[72:73], exec
	s_mov_b32 s5, 0x21e25000
	v_add_co_u32_e32 v94, vcc, s5, v88
	s_cselect_b32 s52, 0x2800, 0
	s_nop 0
	v_addc_co_u32_e32 v95, vcc, 0, v89, vcc
	v_lshl_add_u64 v[82:83], v[82:83], 0, s[52:53]
	v_add_co_u32_e32 v82, vcc, s5, v82
	global_load_dwordx4 v[74:77], v[84:85], off offset:1024
	global_load_dwordx4 v[112:115], v[78:79], off offset:1024
	v_addc_co_u32_e32 v83, vcc, 0, v83, vcc
	global_load_dwordx4 v[100:103], v[86:87], off offset:1024
	global_load_dwordx4 v[78:81], v[86:87], off offset:2048
	s_nop 0
	global_load_dwordx4 v[86:89], v[86:87], off offset:3072
	s_nop 0
	global_load_dwordx4 v[90:93], v[94:95], off offset:2048
	s_nop 0
	global_load_dwordx4 v[94:97], v[94:95], off offset:3072
	s_nop 0
	global_load_dwordx4 v[108:111], v[82:83], off offset:2048
	global_load_dwordx4 v[104:107], v[82:83], off offset:3072
	s_nop 0
	global_load_dwordx4 v[82:85], v[84:85], off
	s_waitcnt vmcnt(10)
	v_lshlrev_b32_e32 v142, 16, v136
	v_and_b32_e32 v143, 0xffff0000, v136
	v_lshlrev_b32_e32 v136, 16, v137
	v_and_b32_e32 v137, 0xffff0000, v137
	v_pk_mul_f32 v[156:157], v[142:143], v[142:143]
	v_pk_mul_f32 v[158:159], v[136:137], v[136:137]
	v_add_f32_e32 v3, v156, v157
	v_lshlrev_b32_e32 v154, 16, v138
	v_and_b32_e32 v155, 0xffff0000, v138
	v_add_f32_e32 v3, v158, v3
	v_pk_mul_f32 v[160:161], v[154:155], v[154:155]
	v_add_f32_e32 v3, v159, v3
	v_and_b32_e32 v140, 0xffff0000, v139
	v_lshlrev_b32_e32 v141, 16, v139
	v_add_f32_e32 v3, v160, v3
	v_pk_mul_f32 v[138:139], v[140:141], v[140:141]
	v_add_f32_e32 v3, v161, v3
	v_add_f32_e32 v3, v139, v3
	v_add_f32_e32 v3, v138, v3
	s_nop 1
	s_waitcnt lgkmcnt(0)
	v_add_f32_dpp v3, v3, v3 quad_perm:[1,0,3,2] row_mask:0xf bank_mask:0xf
	s_nop 1
	s_waitcnt lgkmcnt(0)
	v_add_f32_dpp v3, v3, v3 quad_perm:[2,3,0,1] row_mask:0xf bank_mask:0xf
	s_nop 1
	s_waitcnt lgkmcnt(0)
	v_add_f32_dpp v3, v3, v3 row_half_mirror row_mask:0xf bank_mask:0xf
	s_nop 1
	s_waitcnt lgkmcnt(0)
	v_add_f32_dpp v3, v3, v3 row_mirror row_mask:0xf bank_mask:0xf
	v_fmamk_f32 v3, v3, 0x3c000000, v224
	v_mul_f32_e32 v5, 0x4f800000, v3
	v_cmp_gt_f32_e32 vcc, s33, v3
	s_nop 1
	v_cndmask_b32_e32 v3, v3, v5, vcc
	v_sqrt_f32_e32 v5, v3
	s_nop 0
	v_add_u32_e32 v7, -1, v5
	v_add_u32_e32 v9, 1, v5
	v_fma_f32 v11, -v7, v5, v3
	v_fma_f32 v13, -v9, v5, v3
	v_cmp_ge_f32_e64 s[48:49], 0, v11
	s_nop 1
	v_cndmask_b32_e64 v5, v5, v7, s[48:49]
	v_cmp_lt_f32_e64 s[48:49], 0, v13
	s_nop 1
	v_cndmask_b32_e64 v5, v5, v9, s[48:49]
	v_mul_f32_e32 v7, 0x37800000, v5
	v_cndmask_b32_e32 v5, v5, v7, vcc
	v_cmp_class_f32_e32 vcc, v3, v225
	s_nop 1
	v_cndmask_b32_e32 v3, v5, v3, vcc
	v_div_scale_f32 v5, s[6:7], v3, v3, 1.0
	v_rcp_f32_e32 v7, v5
	v_div_scale_f32 v9, vcc, 1.0, v3, 1.0
	v_fma_f32 v11, -v5, v7, 1.0
	v_fmac_f32_e32 v7, v11, v7
	v_mul_f32_e32 v11, v9, v7
	v_fma_f32 v13, -v5, v11, v9
	v_fmac_f32_e32 v11, v13, v7
	v_fma_f32 v5, -v5, v11, v9
	v_div_fmas_f32 v5, v5, v7, v11
	v_div_fixup_f32 v138, v5, v3, 1.0
	v_pk_mul_f32 v[142:143], v[138:139], v[142:143] op_sel_hi:[0,1]
	v_pk_mul_f32 v[156:157], v[138:139], v[136:137] op_sel_hi:[0,1]
	v_pk_mul_f32 v[154:155], v[138:139], v[154:155] op_sel_hi:[0,1]
	v_pk_mul_f32 v[158:159], v[138:139], v[140:141] op_sel_hi:[0,1]
	s_and_b64 vcc, exec, s[46:47]
	v_pk_mul_f32 v[136:137], v[46:47], v[142:143]
	v_pk_mul_f32 v[138:139], v[48:49], v[156:157]
	v_pk_mul_f32 v[140:141], v[42:43], v[154:155]
	v_pk_mul_f32 v[142:143], v[44:45], v[158:159] op_sel:[0,1] op_sel_hi:[1,0]
	s_cbranch_vccnz .LBB0_380
	ds_bpermute_b32 v154, v149, v136
	ds_bpermute_b32 v155, v149, v137
	v_mov_b32_e32 v158, v59
	v_mov_b32_e32 v159, v61
	v_mov_b32_e32 v156, v58
	v_mov_b32_e32 v157, v60
	s_waitcnt lgkmcnt(0)
	v_pk_mul_f32 v[154:155], v[158:159], v[154:155]
	v_mov_b32_e32 v158, v63
	v_cndmask_b32_e64 v155, v155, -v155, s[42:43]
	v_cndmask_b32_e64 v154, v154, -v154, s[42:43]
	v_pk_fma_f32 v[136:137], v[156:157], v[136:137], v[154:155]
	ds_bpermute_b32 v154, v149, v138
	ds_bpermute_b32 v155, v149, v139
	v_mov_b32_e32 v159, v65
	v_mov_b32_e32 v156, v62
	v_mov_b32_e32 v157, v64
	s_waitcnt lgkmcnt(0)
	v_pk_mul_f32 v[154:155], v[158:159], v[154:155]
	s_nop 0
	v_cndmask_b32_e64 v155, v155, -v155, s[42:43]
	v_cndmask_b32_e64 v154, v154, -v154, s[42:43]
	v_pk_fma_f32 v[138:139], v[156:157], v[138:139], v[154:155]
	ds_bpermute_b32 v154, v149, v140
	ds_bpermute_b32 v155, v149, v141
	v_mov_b32_e32 v158, v67
	v_mov_b32_e32 v159, v69
	v_mov_b32_e32 v156, v66
	v_mov_b32_e32 v157, v68
	s_waitcnt lgkmcnt(0)
	v_pk_mul_f32 v[154:155], v[158:159], v[154:155]
	v_mov_b32_e32 v158, v71
	v_cndmask_b32_e64 v155, v155, -v155, s[42:43]
	v_cndmask_b32_e64 v154, v154, -v154, s[42:43]
	v_pk_fma_f32 v[140:141], v[156:157], v[140:141], v[154:155]
	ds_bpermute_b32 v154, v149, v142
	ds_bpermute_b32 v155, v149, v143
	v_mov_b32_e32 v159, v73
	v_mov_b32_e32 v156, v70
	v_mov_b32_e32 v157, v72
	s_waitcnt lgkmcnt(0)
	v_pk_mul_f32 v[154:155], v[158:159], v[154:155]
	s_nop 0
	v_cndmask_b32_e64 v155, v155, -v155, s[42:43]
	v_cndmask_b32_e64 v154, v154, -v154, s[42:43]
	v_pk_fma_f32 v[142:143], v[156:157], v[142:143], v[154:155]
.LBB0_380:
	v_lshl_add_u64 v[158:159], s[64:65], 0, v[98:99]
	s_mov_b32 s5, 0x35024000
	v_cvt_pk_bf16_f32 v154, v136, v137
	v_add_co_u32_e32 v136, vcc, s5, v158
	v_cvt_pk_bf16_f32 v155, v138, v139
	v_cvt_pk_bf16_f32 v156, v140, v141
	s_waitcnt vmcnt(8)
	v_lshlrev_b32_e32 v140, 16, v112
	v_addc_co_u32_e32 v137, vcc, 0, v159, vcc
	v_and_b32_e32 v141, 0xffff0000, v112
	v_cvt_pk_bf16_f32 v157, v142, v143
	global_store_dwordx4 v[136:137], v[154:157], off
	v_lshlrev_b32_e32 v112, 16, v113
	v_and_b32_e32 v113, 0xffff0000, v113
	v_pk_mul_f32 v[154:155], v[140:141], v[140:141]
	v_pk_mul_f32 v[156:157], v[112:113], v[112:113]
	v_add_f32_e32 v3, v154, v155
	v_lshlrev_b32_e32 v158, 16, v114
	v_and_b32_e32 v159, 0xffff0000, v114
	v_add_f32_e32 v3, v156, v3
	v_and_b32_e32 v142, 0xffff0000, v115
	v_lshlrev_b32_e32 v143, 16, v115
	v_pk_mul_f32 v[114:115], v[158:159], v[158:159]
	v_add_f32_e32 v3, v157, v3
	v_add_f32_e32 v3, v114, v3
	v_pk_mul_f32 v[138:139], v[142:143], v[142:143]
	v_add_f32_e32 v3, v115, v3
	v_add_f32_e32 v3, v139, v3
	v_add_f32_e32 v3, v138, v3
	s_nop 1
	s_waitcnt lgkmcnt(0)
	v_add_f32_dpp v3, v3, v3 quad_perm:[1,0,3,2] row_mask:0xf bank_mask:0xf
	s_nop 1
	s_waitcnt lgkmcnt(0)
	v_add_f32_dpp v3, v3, v3 quad_perm:[2,3,0,1] row_mask:0xf bank_mask:0xf
	s_nop 1
	s_waitcnt lgkmcnt(0)
	v_add_f32_dpp v3, v3, v3 row_half_mirror row_mask:0xf bank_mask:0xf
	s_nop 1
	s_waitcnt lgkmcnt(0)
	v_add_f32_dpp v3, v3, v3 row_mirror row_mask:0xf bank_mask:0xf
	v_fmamk_f32 v3, v3, 0x3c000000, v224
	v_cmp_gt_f32_e32 vcc, s33, v3
	v_mul_f32_e32 v5, 0x4f800000, v3
	s_nop 0
	v_cndmask_b32_e32 v3, v3, v5, vcc
	v_sqrt_f32_e32 v5, v3
	s_nop 0
	v_add_u32_e32 v7, -1, v5
	v_fma_f32 v9, -v7, v5, v3
	v_cmp_ge_f32_e64 s[48:49], 0, v9
	v_add_u32_e32 v9, 1, v5
	s_nop 0
	v_cndmask_b32_e64 v7, v5, v7, s[48:49]
	v_fma_f32 v5, -v9, v5, v3
	v_cmp_lt_f32_e64 s[48:49], 0, v5
	s_nop 1
	v_cndmask_b32_e64 v5, v7, v9, s[48:49]
	v_mul_f32_e32 v7, 0x37800000, v5
	v_cndmask_b32_e32 v5, v5, v7, vcc
	v_cmp_class_f32_e32 vcc, v3, v225
	s_nop 1
	v_cndmask_b32_e32 v3, v5, v3, vcc
	v_div_scale_f32 v5, s[6:7], v3, v3, 1.0
	v_rcp_f32_e32 v7, v5
	s_nop 0
	v_fma_f32 v9, -v5, v7, 1.0
	v_fmac_f32_e32 v7, v9, v7
	v_div_scale_f32 v9, vcc, 1.0, v3, 1.0
	v_mul_f32_e32 v11, v9, v7
	v_fma_f32 v13, -v5, v11, v9
	v_fmac_f32_e32 v11, v13, v7
	v_fma_f32 v5, -v5, v11, v9
	v_div_fmas_f32 v5, v5, v7, v11
	v_div_fixup_f32 v154, v5, v3, 1.0
	v_pk_mul_f32 v[112:113], v[154:155], v[112:113] op_sel_hi:[0,1]
	v_pk_mul_f32 v[114:115], v[154:155], v[140:141] op_sel_hi:[0,1]
	v_pk_mul_f32 v[138:139], v[48:49], v[112:113]
	v_pk_mul_f32 v[112:113], v[154:155], v[158:159] op_sel_hi:[0,1]
	v_pk_mul_f32 v[140:141], v[46:47], v[114:115]
	v_pk_mul_f32 v[114:115], v[42:43], v[112:113]
	v_pk_mul_f32 v[112:113], v[154:155], v[142:143] op_sel_hi:[0,1]
	v_pk_mul_f32 v[112:113], v[44:45], v[112:113] op_sel:[0,1] op_sel_hi:[1,0]
	s_and_b64 vcc, exec, s[46:47]
	s_cbranch_vccnz .LBB0_367
	ds_bpermute_b32 v142, v149, v140
	ds_bpermute_b32 v143, v149, v141
	v_mov_b32_e32 v156, v59
	v_mov_b32_e32 v157, v61
	v_mov_b32_e32 v154, v58
	v_mov_b32_e32 v155, v60
	s_waitcnt lgkmcnt(0)
	v_pk_mul_f32 v[142:143], v[156:157], v[142:143]
	v_mov_b32_e32 v156, v63
	v_cndmask_b32_e64 v143, v143, -v143, s[42:43]
	v_cndmask_b32_e64 v142, v142, -v142, s[42:43]
	v_pk_fma_f32 v[140:141], v[154:155], v[140:141], v[142:143]
	ds_bpermute_b32 v142, v149, v138
	ds_bpermute_b32 v143, v149, v139
	v_mov_b32_e32 v157, v65
	v_mov_b32_e32 v154, v62
	v_mov_b32_e32 v155, v64
	s_waitcnt lgkmcnt(0)
	v_pk_mul_f32 v[142:143], v[156:157], v[142:143]
	s_nop 0
	v_cndmask_b32_e64 v143, v143, -v143, s[42:43]
	v_cndmask_b32_e64 v142, v142, -v142, s[42:43]
	v_pk_fma_f32 v[138:139], v[154:155], v[138:139], v[142:143]
	ds_bpermute_b32 v142, v149, v114
	ds_bpermute_b32 v143, v149, v115
	v_mov_b32_e32 v156, v67
	v_mov_b32_e32 v157, v69
	v_mov_b32_e32 v154, v66
	v_mov_b32_e32 v155, v68
	s_waitcnt lgkmcnt(0)
	v_pk_mul_f32 v[142:143], v[156:157], v[142:143]
	v_mov_b32_e32 v156, v71
	v_cndmask_b32_e64 v143, v143, -v143, s[42:43]
	v_cndmask_b32_e64 v142, v142, -v142, s[42:43]
	v_pk_fma_f32 v[114:115], v[154:155], v[114:115], v[142:143]
	ds_bpermute_b32 v142, v149, v112
	ds_bpermute_b32 v143, v149, v113
	v_mov_b32_e32 v157, v73
	v_mov_b32_e32 v154, v70
	v_mov_b32_e32 v155, v72
	s_waitcnt lgkmcnt(0)
	v_pk_mul_f32 v[142:143], v[156:157], v[142:143]
	s_nop 0
	v_cndmask_b32_e64 v143, v143, -v143, s[42:43]
	v_cndmask_b32_e64 v142, v142, -v142, s[42:43]
	v_pk_fma_f32 v[112:113], v[154:155], v[112:113], v[142:143]
	s_branch .LBB0_367
